# PA-deepK-plus-Qwait-fold
# speedup vs baseline: 1.0053x; 1.0038x over previous
; #define GAS __attribute__((address_space(1)))
; __device__ __forceinline__ int opq(int x) { asm volatile("" : "+v"(x)); return x; }
; __device__ __forceinline__ void attn_unit(const bf16* Q, const bf16* K, const bf16* V, bf16* O, int b, int h, int qb, float sref, LAS unsigned char* lds, int wave, int lane_) {
;     const int lane = opq(lane_), r32 = lane & 31, hi = lane >> 5;
;     const size_t rowbase = (size_t)b * SEQ; const int q0 = qb * 256, qw = q0 + wave * 32;
;     const bf16* Kg = K + rowbase * 768 + h * QKH; const bf16* Vg = V + rowbase * 1024 + h * VH;
;     const int NT = (q0 + 256) / 64;
;     bf16x8 qf[6];
;     { const bf16* qp = Q + (rowbase + qw + r32) * 768 + h * QKH + hi * 8;
; #pragma unroll
;       for (int s = 0; s < 6; ++s) qf[s] = *(const GAS bf16x8*)(qp + 16 * s); }
;     asm volatile("s_waitcnt vmcnt(0)" ::: "memory");
; #pragma unroll
;     for (int s = 0; s < 6; ++s) asm volatile("" : "+v"(qf[s]));
;     issue_tile(Kg, Vg, lds, 0, wave, lane); issue_tile(Kg, Vg, lds + SLOT, 64, wave, lane);
.LBB0_1389:
	s_lshl_b32 s0, s66, 8
	s_ashr_i32 s16, s66, 7
	s_and_b32 s0, s0, 0xf00
	s_ashr_i32 s17, s16, 31
	s_add_i32 s33, s0, s58
	s_bfe_u32 s1, s66, 0x30004
	v_mov_b32_e32 v159, v198
	s_lshl_b64 s[26:27], s[16:17], 13
	s_ashr_i32 s8, s33, 31
	s_add_u32 s9, s26, s33
	v_and_b32_e32 v26, 31, v159
	v_or_b32_e32 v156, s9, v26
	v_ashrrev_i32_e32 v27, 5, v159
	s_mul_i32 s12, s1, 0x60
	s_addc_u32 s22, s27, s8
	v_mad_u64_u32 v[20:21], s[8:9], v156, s65, v[154:155]
	v_mad_i32_i24 v21, s22, v164, v21
	s_lshl_b32 s12, s12, 1
	v_lshlrev_b32_e32 v22, 3, v27
	v_lshl_add_u64 v[20:21], v[20:21], 0, s[12:13]
	v_ashrrev_i32_e32 v23, 31, v22
	v_lshl_add_u64 v[20:21], v[22:23], 1, v[20:21]
	global_load_dwordx4 v[130:133], v[20:21], off
	global_load_dwordx4 v[134:137], v[20:21], off offset:32
	global_load_dwordx4 v[138:141], v[20:21], off offset:64
	global_load_dwordx4 v[142:145], v[20:21], off offset:96
	global_load_dwordx4 v[146:149], v[20:21], off offset:128
	global_load_dwordx4 v[150:153], v[20:21], off offset:160
	s_mul_i32 s9, s16, 0xc00000
	s_mul_hi_i32 s8, s16, 0xc00000
	s_add_u32 s9, s54, s9
	s_addc_u32 s8, s55, s8
	s_add_u32 s24, s9, s12
	s_addc_u32 s25, s8, 0
	v_mov_b64_e32 v[20:21], s[24:25]
	v_mad_i64_i32 v[20:21], s[8:9], v159, s65, v[20:21]
	v_readfirstlane_b32 s34, v165
	v_lshl_add_u64 v[20:21], s[10:11], 1, v[20:21]
	v_mov_b32_e32 v157, s22
	s_and_b64 vcc, exec, s[2:3]
	s_mov_b32 s8, m0
	s_mov_b32 m0, s34
	s_nop 0
	global_load_lds_dwordx4 v[20:21], off
	s_mov_b32 m0, s8
	s_cbranch_vccnz .LBB0_1391
	v_lshl_add_u64 v[20:21], v[20:21], 0, s[30:31]
	s_add_i32 s8, s60, 0x2000
	s_mov_b32 s9, m0
	s_mov_b32 m0, s8
	s_nop 0
	global_load_lds_dwordx4 v[20:21], off
	s_mov_b32 m0, s9

; #define GAS __attribute__((address_space(1)))
; __device__ __forceinline__ unsigned cvt_pk_bf16(float lo, float hi) { unsigned r; asm volatile("v_cvt_pk_bf16_f32 %0, %1, %2" : "=v"(r) : "v"(lo), "v"(hi)); return r; }
; __device__ __forceinline__ float swap_sum(float v) { auto rr = __builtin_amdgcn_permlane32_swap(__float_as_uint(v), __float_as_uint(v), false, false); return __uint_as_float(rr[0]) + __uint_as_float(rr[1]); }
; __device__ __forceinline__ void attn_unit(const bf16* Q, const bf16* K, const bf16* V, bf16* O, int b, int h, int qb, float sref, LAS unsigned char* lds, int wave, int lane_) {
;     ...
;     PA_PV(pB0, pB1, s1);
;     ...
;     const float il = 1.0f / swap_sum(l);
;     bf16* op = O + (rowbase + qw + r32) * ATTW + h * VH + 4 * hi;
; #pragma unroll
;     for (int g = 0; g < 4; ++g) {
;         v2u w0, w1; w0.x = cvt_pk_bf16(o0[4 * g] * il, o0[4 * g + 1] * il); w0.y = cvt_pk_bf16(o0[4 * g + 2] * il, o0[4 * g + 3] * il);
;         w1.x = cvt_pk_bf16(o1[4 * g] * il, o1[4 * g + 1] * il); w1.y = cvt_pk_bf16(o1[4 * g + 2] * il, o1[4 * g + 3] * il);
;         *(GAS v2u*)(op + 8 * g) = w0; *(GAS v2u*)(op + 32 + 8 * g) = w1;
;     }
;     asm volatile("s_waitcnt vmcnt(0) lgkmcnt(0)" ::: "memory");
;     __syncthreads();
.LBB0_1417:
	s_mul_i32 s22, s83, 0x5000
	s_add_i32 s22, s22, 0
	v_add_u32_e32 v73, s22, v172
	v_exp_f32_e32 v33, v114
	v_exp_f32_e32 v18, v115
	v_exp_f32_e32 v67, v116
	v_exp_f32_e32 v32, v117
	v_exp_f32_e32 v69, v118
	v_exp_f32_e32 v66, v119
	v_exp_f32_e32 v71, v120
	v_exp_f32_e32 v68, v121
	v_cvt_pk_bf16_f32 v20, v33, v18
	v_cvt_pk_bf16_f32 v21, v67, v32
	v_cvt_pk_bf16_f32 v22, v69, v66
	v_cvt_pk_bf16_f32 v23, v71, v68
	ds_read_b64_tr_b16 v[24:25], v73 offset:12288
	ds_read_b64_tr_b16 v[26:27], v73 offset:12800
	ds_read_b64_tr_b16 v[28:29], v73 offset:16384
	ds_read_b64_tr_b16 v[30:31], v73 offset:16896
	s_waitcnt lgkmcnt(2)
	v_mfma_f32_32x32x16_bf16 v[50:65], v[24:27], v[20:23], v[50:65]
	v_exp_f32_e32 v75, v122
	v_exp_f32_e32 v70, v123
	v_exp_f32_e32 v77, v124
	v_exp_f32_e32 v72, v125
	v_exp_f32_e32 v79, v126
	v_exp_f32_e32 v74, v127
	v_exp_f32_e32 v81, v128
	v_exp_f32_e32 v76, v129
	s_waitcnt lgkmcnt(0)
	v_mfma_f32_32x32x16_bf16 v[34:49], v[28:31], v[20:23], v[34:49]
	v_cvt_pk_bf16_f32 v20, v75, v70
	v_cvt_pk_bf16_f32 v21, v77, v72
	v_cvt_pk_bf16_f32 v22, v79, v74
	v_cvt_pk_bf16_f32 v23, v81, v76
	ds_read_b64_tr_b16 v[24:25], v73 offset:13312
	ds_read_b64_tr_b16 v[26:27], v73 offset:13824
	ds_read_b64_tr_b16 v[28:29], v73 offset:17408
	ds_read_b64_tr_b16 v[30:31], v73 offset:17920
	v_exp_f32_e32 v94, v98
	s_waitcnt lgkmcnt(2)
	v_mfma_f32_32x32x16_bf16 v[50:65], v[24:27], v[20:23], v[50:65]
	v_exp_f32_e32 v78, v99
	v_exp_f32_e32 v95, v100
	v_exp_f32_e32 v80, v101
	v_exp_f32_e32 v83, v102
	v_exp_f32_e32 v82, v103
	v_exp_f32_e32 v85, v104
	v_exp_f32_e32 v84, v105
	s_waitcnt lgkmcnt(0)
	v_mfma_f32_32x32x16_bf16 v[34:49], v[28:31], v[20:23], v[34:49]
	v_cvt_pk_bf16_f32 v20, v94, v78
	v_cvt_pk_bf16_f32 v21, v95, v80
	v_cvt_pk_bf16_f32 v22, v83, v82
	v_cvt_pk_bf16_f32 v23, v85, v84
	ds_read_b64_tr_b16 v[24:25], v73 offset:14336
	ds_read_b64_tr_b16 v[26:27], v73 offset:14848
	ds_read_b64_tr_b16 v[28:29], v73 offset:18432
	ds_read_b64_tr_b16 v[30:31], v73 offset:18944
	v_exp_f32_e32 v91, v110
	s_waitcnt lgkmcnt(2)
	v_mfma_f32_32x32x16_bf16 v[50:65], v[24:27], v[20:23], v[50:65]
	v_exp_f32_e32 v87, v106
	v_exp_f32_e32 v86, v107
	v_exp_f32_e32 v89, v108
	v_exp_f32_e32 v88, v109
	v_exp_f32_e32 v90, v111
	v_exp_f32_e32 v93, v112
	v_exp_f32_e32 v92, v113
	s_waitcnt lgkmcnt(0)
	v_mfma_f32_32x32x16_bf16 v[34:49], v[28:31], v[20:23], v[34:49]
	v_cvt_pk_bf16_f32 v20, v87, v86
	v_cvt_pk_bf16_f32 v21, v89, v88
	v_cvt_pk_bf16_f32 v22, v91, v90
	v_cvt_pk_bf16_f32 v23, v93, v92
	ds_read_b64_tr_b16 v[24:25], v73 offset:15360
	ds_read_b64_tr_b16 v[26:27], v73 offset:15872
	ds_read_b64_tr_b16 v[28:29], v73 offset:19456
	ds_read_b64_tr_b16 v[30:31], v73 offset:19968
	v_add_f32_e32 v91, v91, v79
	v_add_f32_e32 v79, v94, v33
	s_waitcnt lgkmcnt(2)
	v_mfma_f32_32x32x16_bf16 v[50:65], v[24:27], v[20:23], v[50:65]
	v_add_f32_e64 v24, v78, v18
	v_add_f32_e64 v25, v79, v19
	v_add_f32_e32 v93, v93, v81
	v_pk_add_f32 v[24:25], v[24:25], v[24:25] op_sel_hi:[0,1]
	v_add_f32_e32 v81, v95, v67
	v_mov_b32_e32 v33, v25
	v_pk_add_f32 v[24:25], v[80:81], v[32:33]
	v_add_f32_e32 v83, v83, v69
	v_pk_add_f32 v[24:25], v[24:25], v[24:25] op_sel_hi:[0,1]
	v_mov_b32_e32 v67, v25
	v_pk_add_f32 v[24:25], v[82:83], v[66:67]
	v_add_f32_e32 v85, v85, v71
	v_pk_add_f32 v[24:25], v[24:25], v[24:25] op_sel_hi:[0,1]
	v_mov_b32_e32 v69, v25
	v_pk_add_f32 v[24:25], v[84:85], v[68:69]
	v_add_f32_e32 v87, v87, v75
	v_pk_add_f32 v[24:25], v[24:25], v[24:25] op_sel_hi:[0,1]
	v_mov_b32_e32 v71, v25
	v_pk_add_f32 v[24:25], v[86:87], v[70:71]
	v_add_f32_e32 v89, v89, v77
	v_pk_add_f32 v[24:25], v[24:25], v[24:25] op_sel_hi:[0,1]
	v_mov_b32_e32 v73, v25
	v_pk_add_f32 v[24:25], v[88:89], v[72:73]
	s_waitcnt lgkmcnt(0)
	v_mfma_f32_32x32x16_bf16 v[34:49], v[28:31], v[20:23], v[34:49]
	v_pk_add_f32 v[24:25], v[24:25], v[24:25] op_sel_hi:[0,1]
	v_mov_b32_e32 v75, v25
	v_pk_add_f32 v[24:25], v[90:91], v[74:75]
	v_ashrrev_i32_e32 v159, 31, v158
	v_pk_add_f32 v[24:25], v[24:25], v[24:25] op_sel_hi:[0,1]
	v_mov_b32_e32 v77, v25
	v_pk_add_f32 v[24:25], v[92:93], v[76:77]
	s_xor_b32 s22, s0, 0x1f00
	v_add_f32_e32 v18, v24, v25
	v_add_f32_e32 v18, v170, v18
	v_mov_b32_e32 v24, v18
	s_nop 1
	v_permlane32_swap_b32_e32 v18, v24
	v_add_f32_e32 v18, v18, v24
	v_div_scale_f32 v24, s[52:53], v18, v18, 1.0
	v_rcp_f32_e32 v25, v24
	s_lshl_b32 s52, s67, 1
	s_mov_b32 s53, s13
	s_add_i32 s0, s22, s58
	v_fma_f32 v20, -v24, v25, 1.0
	v_fmac_f32_e32 v25, v20, v25
	v_div_scale_f32 v20, vcc, 1.0, v18, 1.0
	v_mul_f32_e32 v21, v20, v25
	v_fma_f32 v22, -v24, v21, v20
	v_fmac_f32_e32 v21, v22, v25
	v_fma_f32 v20, -v24, v21, v20
	v_div_fmas_f32 v20, v20, v25, v21
	v_div_fixup_f32 v18, v20, v18, 1.0
	v_lshlrev_b64 v[20:21], 10, v[156:157]
	v_mul_f32_e32 v22, v50, v18
	v_mul_f32_e32 v23, v51, v18
	v_lshl_add_u64 v[20:21], s[6:7], 0, v[20:21]
	v_cvt_pk_bf16_f32 v22, v22, v23
	v_mul_f32_e32 v23, v52, v18
	v_mul_f32_e32 v24, v53, v18
	v_lshl_add_u64 v[20:21], v[20:21], 0, s[52:53]
	v_cvt_pk_bf16_f32 v23, v23, v24
	v_mul_f32_e32 v24, v34, v18
	v_mul_f32_e32 v25, v35, v18
	v_lshl_add_u64 v[20:21], v[158:159], 1, v[20:21]
	v_cvt_pk_bf16_f32 v24, v24, v25
	v_mul_f32_e32 v25, v36, v18
	v_mul_f32_e32 v26, v37, v18
	v_cvt_pk_bf16_f32 v25, v25, v26
	global_store_dwordx2 v[20:21], v[22:23], off
	global_store_dwordx2 v[20:21], v[24:25], off offset:64
	v_mul_f32_e32 v22, v54, v18
	v_mul_f32_e32 v23, v55, v18
	v_cvt_pk_bf16_f32 v22, v22, v23
	v_mul_f32_e32 v23, v56, v18
	v_mul_f32_e32 v24, v57, v18
	v_cvt_pk_bf16_f32 v23, v23, v24
	v_mul_f32_e32 v24, v38, v18
	v_mul_f32_e32 v25, v39, v18
	v_cvt_pk_bf16_f32 v24, v24, v25
	v_mul_f32_e32 v25, v40, v18
	v_mul_f32_e32 v26, v41, v18
	v_cvt_pk_bf16_f32 v25, v25, v26
	global_store_dwordx2 v[20:21], v[22:23], off offset:16
	global_store_dwordx2 v[20:21], v[24:25], off offset:80
	v_mul_f32_e32 v22, v58, v18
	v_mul_f32_e32 v23, v59, v18
	v_cvt_pk_bf16_f32 v22, v22, v23
	v_mul_f32_e32 v23, v60, v18
	v_mul_f32_e32 v24, v61, v18
	v_cvt_pk_bf16_f32 v23, v23, v24
	v_mul_f32_e32 v24, v42, v18
	v_mul_f32_e32 v25, v43, v18
	v_cvt_pk_bf16_f32 v24, v24, v25
	v_mul_f32_e32 v25, v44, v18
	v_mul_f32_e32 v26, v45, v18
	v_cvt_pk_bf16_f32 v25, v25, v26
	global_store_dwordx2 v[20:21], v[22:23], off offset:32
	global_store_dwordx2 v[20:21], v[24:25], off offset:96
	v_mul_f32_e32 v22, v62, v18
	v_mul_f32_e32 v23, v63, v18
	v_cvt_pk_bf16_f32 v22, v22, v23
	v_mul_f32_e32 v23, v64, v18
	v_mul_f32_e32 v24, v65, v18
	v_cvt_pk_bf16_f32 v23, v23, v24
	v_mul_f32_e32 v24, v46, v18
	v_mul_f32_e32 v25, v47, v18
	v_cvt_pk_bf16_f32 v24, v24, v25
	v_mul_f32_e32 v25, v48, v18
	v_mul_f32_e32 v18, v49, v18
	v_cvt_pk_bf16_f32 v25, v25, v18
	global_store_dwordx2 v[20:21], v[22:23], off offset:48
	global_store_dwordx2 v[20:21], v[24:25], off offset:112
	v_mov_b32_e32 v159, v198
	s_ashr_i32 s33, s0, 31
	s_waitcnt vmcnt(0) lgkmcnt(0)
	s_barrier
; #define GAS __attribute__((address_space(1)))
; __device__ __forceinline__ int opq(int x) { asm volatile("" : "+v"(x)); return x; }
; __device__ __forceinline__ void attn_unit(const bf16* Q, const bf16* K, const bf16* V, bf16* O, int b, int h, int qb, float sref, LAS unsigned char* lds, int wave, int lane_) {
;     const int lane = opq(lane_), r32 = lane & 31, hi = lane >> 5;
;     const size_t rowbase = (size_t)b * SEQ; const int q0 = qb * 256, qw = q0 + wave * 32;
;     const bf16* Kg = K + rowbase * 768 + h * QKH; const bf16* Vg = V + rowbase * 1024 + h * VH;
;     const int NT = (q0 + 256) / 64;
;     bf16x8 qf[6];
;     { const bf16* qp = Q + (rowbase + qw + r32) * 768 + h * QKH + hi * 8;
; #pragma unroll
;       for (int s = 0; s < 6; ++s) qf[s] = *(const GAS bf16x8*)(qp + 16 * s); }
;     asm volatile("s_waitcnt vmcnt(0)" ::: "memory");
; #pragma unroll
;     for (int s = 0; s < 6; ++s) asm volatile("" : "+v"(qf[s]));
;     issue_tile(Kg, Vg, lds, 0, wave, lane); issue_tile(Kg, Vg, lds + SLOT, 64, wave, lane);
	s_add_u32 s26, s26, s0
	v_and_b32_e32 v26, 31, v159
	v_or_b32_e32 v156, s26, v26
	v_mov_b64_e32 v[20:21], s[4:5]
	v_ashrrev_i32_e32 v27, 5, v159
	s_addc_u32 s33, s27, s33
	v_mad_u64_u32 v[20:21], s[26:27], v156, s65, v[20:21]
	v_mad_i32_i24 v21, s33, v164, v21
	v_lshlrev_b32_e32 v22, 3, v27
	v_lshl_add_u64 v[20:21], v[20:21], 0, s[12:13]
	v_ashrrev_i32_e32 v23, 31, v22
	v_lshl_add_u64 v[20:21], v[22:23], 1, v[20:21]
	global_load_dwordx4 v[130:133], v[20:21], off
	global_load_dwordx4 v[134:137], v[20:21], off offset:32
	global_load_dwordx4 v[138:141], v[20:21], off offset:64
	global_load_dwordx4 v[142:145], v[20:21], off offset:96
	global_load_dwordx4 v[146:149], v[20:21], off offset:128
	global_load_dwordx4 v[150:153], v[20:21], off offset:160
	v_mov_b64_e32 v[20:21], s[24:25]
	v_mad_i64_i32 v[20:21], s[26:27], v159, s65, v[20:21]
	v_lshl_add_u64 v[20:21], s[10:11], 1, v[20:21]
	s_mov_b32 s12, m0
	s_mov_b32 m0, s60
	s_nop 0
	global_load_lds_dwordx4 v[20:21], off
	s_mov_b32 m0, s12
	v_mov_b32_e32 v157, s33
	s_and_b64 vcc, exec, s[2:3]
	s_cbranch_vccnz .LBB0_1419
	v_lshl_add_u64 v[20:21], v[20:21], 0, s[30:31]
	s_add_i32 s12, s60, 0x2000
	s_mov_b32 s26, m0
	s_mov_b32 m0, s12
	s_nop 0
	global_load_lds_dwordx4 v[20:21], off
	s_mov_b32 m0, s26
